# layer-1 GEMM2 epilogue: DPP row exchange so every f32 store instruction writes full 128-byte lines (8 rows x 128 B)
# speedup vs baseline: 1.5097x; 1.0005x over previous
;     __device__ __forceinline__ void operator()(const f32x4 (&acc)[2][2][4][2], const pg8::Unit& u, int, LAS unsigned char*, int wr, int wc, int fr_, int fq_) const {
;     ...
;         } else {
;             f16x8 xh[2][4][2];
; #pragma unroll
;             for (int ai = 0; ai < 2; ++ai)
; #pragma unroll
;                 for (int m = 0; m < 4; ++m)
; #pragma unroll
;                     for (int bj = 0; bj < 2; ++bj) xh[ai][m][bj] = *(const f16x8*)(XH + (size_t)(row0 + ai * 128 + m * 16) * DM + col0 + bj * 32);
; #pragma unroll
;             for (int ai = 0; ai < 2; ++ai)
; #pragma unroll
;                 for (int m = 0; m < 4; ++m) {
;                     float* dst = out + (size_t)(row0 + ai * 128 + m * 16) * DM + col0;
; #pragma unroll
;                     for (int bj = 0; bj < 2; ++bj) {
;                         f32x4 x0, x1;
; #pragma unroll
;                         for (int e = 0; e < 4; ++e) { x0[e] = (float)xh[ai][m][bj][e] + acc[ai][bj][m][0][e]; x1[e] = (float)xh[ai][m][bj][4 + e] + acc[ai][bj][m][1][e]; }
;                         *(f32x4*)(dst + bj * 32) = x0; *(f32x4*)(dst + bj * 32 + 4) = x1;
;                     }
;                 }
.LBB0_503:
	v_and_b32_e32 v190, 8, v186
	v_and_b32_e32 v186, 0xfffffff7, v186
	v_ashrrev_i32_e32 v187, 31, v186
	v_lshlrev_b64 v[192:193], 12, v[186:187]
	v_lshl_add_u64 v[196:197], s[38:39], 0, v[192:193]
	v_lshlrev_b32_e32 v192, 2, v188
	v_lshlrev_b32_e32 v193, 4, v234
	v_sub_u32_e32 v192, v192, v193
	v_lshl_add_u32 v192, v190, 3, v192
	v_mov_b32_e32 v193, 0
	v_lshl_add_u64 v[196:197], v[196:197], 0, v[192:193]
	s_mov_b64 s[100:101], 0x8000
	v_lshl_add_u64 v[192:193], v[196:197], 0, s[100:101]
	s_mov_b64 s[100:101], 0x10000
	s_nop 1
	v_permlane16_swap_b32_e32 v126, v122
	v_permlane16_swap_b32_e32 v127, v123
	v_permlane16_swap_b32_e32 v128, v124
	v_permlane16_swap_b32_e32 v129, v125
	v_permlane32_swap_b32_e32 v126, v122
	v_permlane32_swap_b32_e32 v127, v123
	v_permlane32_swap_b32_e32 v128, v124
	v_permlane32_swap_b32_e32 v129, v125
	v_mov_b32_e32 v236, v126
	v_mov_b32_e32 v237, v127
	v_mov_b32_e32 v238, v128
	v_mov_b32_e32 v239, v129
	v_mov_b32_dpp v126, v122 row_ror:8 row_mask:0xf bank_mask:0xc
	v_mov_b32_dpp v127, v123 row_ror:8 row_mask:0xf bank_mask:0xc
	v_mov_b32_dpp v128, v124 row_ror:8 row_mask:0xf bank_mask:0xc
	v_mov_b32_dpp v129, v125 row_ror:8 row_mask:0xf bank_mask:0xc
	v_mov_b32_dpp v122, v236 row_ror:8 row_mask:0xf bank_mask:0x3
	v_mov_b32_dpp v123, v237 row_ror:8 row_mask:0xf bank_mask:0x3
	v_mov_b32_dpp v124, v238 row_ror:8 row_mask:0xf bank_mask:0x3
	v_mov_b32_dpp v125, v239 row_ror:8 row_mask:0xf bank_mask:0x3
	global_store_dwordx4 v[196:197], v[126:129], off
	global_store_dwordx4 v[192:193], v[122:125], off
	v_permlane16_swap_b32_e32 v118, v114
	v_permlane16_swap_b32_e32 v119, v115
	v_permlane16_swap_b32_e32 v120, v116
	v_permlane16_swap_b32_e32 v121, v117
	v_permlane32_swap_b32_e32 v118, v114
	v_permlane32_swap_b32_e32 v119, v115
	v_permlane32_swap_b32_e32 v120, v116
	v_permlane32_swap_b32_e32 v121, v117
	v_mov_b32_e32 v236, v118
	v_mov_b32_e32 v237, v119
	v_mov_b32_e32 v238, v120
	v_mov_b32_e32 v239, v121
	v_mov_b32_dpp v118, v114 row_ror:8 row_mask:0xf bank_mask:0xc
	v_mov_b32_dpp v119, v115 row_ror:8 row_mask:0xf bank_mask:0xc
	v_mov_b32_dpp v120, v116 row_ror:8 row_mask:0xf bank_mask:0xc
	v_mov_b32_dpp v121, v117 row_ror:8 row_mask:0xf bank_mask:0xc
	v_mov_b32_dpp v114, v236 row_ror:8 row_mask:0xf bank_mask:0x3
	v_mov_b32_dpp v115, v237 row_ror:8 row_mask:0xf bank_mask:0x3
	v_mov_b32_dpp v116, v238 row_ror:8 row_mask:0xf bank_mask:0x3
	v_mov_b32_dpp v117, v239 row_ror:8 row_mask:0xf bank_mask:0x3
	global_store_dwordx4 v[196:197], v[118:121], off offset:128
	global_store_dwordx4 v[192:193], v[114:117], off offset:128
	v_lshl_add_u64 v[196:197], v[196:197], 0, s[100:101]
	v_lshl_add_u64 v[192:193], v[192:193], 0, s[100:101]
	v_permlane16_swap_b32_e32 v110, v106
	v_permlane16_swap_b32_e32 v111, v107
	v_permlane16_swap_b32_e32 v112, v108
	v_permlane16_swap_b32_e32 v113, v109
	v_permlane32_swap_b32_e32 v110, v106
	v_permlane32_swap_b32_e32 v111, v107
	v_permlane32_swap_b32_e32 v112, v108
	v_permlane32_swap_b32_e32 v113, v109
	v_mov_b32_e32 v236, v110
	v_mov_b32_e32 v237, v111
	v_mov_b32_e32 v238, v112
	v_mov_b32_e32 v239, v113
	v_mov_b32_dpp v110, v106 row_ror:8 row_mask:0xf bank_mask:0xc
	v_mov_b32_dpp v111, v107 row_ror:8 row_mask:0xf bank_mask:0xc
	v_mov_b32_dpp v112, v108 row_ror:8 row_mask:0xf bank_mask:0xc
	v_mov_b32_dpp v113, v109 row_ror:8 row_mask:0xf bank_mask:0xc
	v_mov_b32_dpp v106, v236 row_ror:8 row_mask:0xf bank_mask:0x3
	v_mov_b32_dpp v107, v237 row_ror:8 row_mask:0xf bank_mask:0x3
	v_mov_b32_dpp v108, v238 row_ror:8 row_mask:0xf bank_mask:0x3
	v_mov_b32_dpp v109, v239 row_ror:8 row_mask:0xf bank_mask:0x3
	global_store_dwordx4 v[196:197], v[110:113], off
	global_store_dwordx4 v[192:193], v[106:109], off
	v_permlane16_swap_b32_e32 v102, v98
	v_permlane16_swap_b32_e32 v103, v99
	v_permlane16_swap_b32_e32 v104, v100
	v_permlane16_swap_b32_e32 v105, v101
	v_permlane32_swap_b32_e32 v102, v98
	v_permlane32_swap_b32_e32 v103, v99
	v_permlane32_swap_b32_e32 v104, v100
	v_permlane32_swap_b32_e32 v105, v101
	v_mov_b32_e32 v236, v102
	v_mov_b32_e32 v237, v103
	v_mov_b32_e32 v238, v104
	v_mov_b32_e32 v239, v105
	v_mov_b32_dpp v102, v98 row_ror:8 row_mask:0xf bank_mask:0xc
	v_mov_b32_dpp v103, v99 row_ror:8 row_mask:0xf bank_mask:0xc
	v_mov_b32_dpp v104, v100 row_ror:8 row_mask:0xf bank_mask:0xc
	v_mov_b32_dpp v105, v101 row_ror:8 row_mask:0xf bank_mask:0xc
	v_mov_b32_dpp v98, v236 row_ror:8 row_mask:0xf bank_mask:0x3
	v_mov_b32_dpp v99, v237 row_ror:8 row_mask:0xf bank_mask:0x3
	v_mov_b32_dpp v100, v238 row_ror:8 row_mask:0xf bank_mask:0x3
	v_mov_b32_dpp v101, v239 row_ror:8 row_mask:0xf bank_mask:0x3
	global_store_dwordx4 v[196:197], v[102:105], off offset:128
	global_store_dwordx4 v[192:193], v[98:101], off offset:128
	v_lshl_add_u64 v[196:197], v[196:197], 0, s[100:101]
	v_lshl_add_u64 v[192:193], v[192:193], 0, s[100:101]
	v_permlane16_swap_b32_e32 v94, v90
	v_permlane16_swap_b32_e32 v95, v91
	v_permlane16_swap_b32_e32 v96, v92
	v_permlane16_swap_b32_e32 v97, v93
	v_permlane32_swap_b32_e32 v94, v90
	v_permlane32_swap_b32_e32 v95, v91
	v_permlane32_swap_b32_e32 v96, v92
	v_permlane32_swap_b32_e32 v97, v93
	v_mov_b32_e32 v236, v94
	v_mov_b32_e32 v237, v95
	v_mov_b32_e32 v238, v96
	v_mov_b32_e32 v239, v97
	v_mov_b32_dpp v94, v90 row_ror:8 row_mask:0xf bank_mask:0xc
	v_mov_b32_dpp v95, v91 row_ror:8 row_mask:0xf bank_mask:0xc
	v_mov_b32_dpp v96, v92 row_ror:8 row_mask:0xf bank_mask:0xc
	v_mov_b32_dpp v97, v93 row_ror:8 row_mask:0xf bank_mask:0xc
	v_mov_b32_dpp v90, v236 row_ror:8 row_mask:0xf bank_mask:0x3
	v_mov_b32_dpp v91, v237 row_ror:8 row_mask:0xf bank_mask:0x3
	v_mov_b32_dpp v92, v238 row_ror:8 row_mask:0xf bank_mask:0x3
;     __device__ __forceinline__ void operator()(const f32x4 (&acc)[2][2][4][2], const pg8::Unit& u, int, LAS unsigned char*, int wr, int wc, int fr_, int fq_) const {
;     ...
;         } else {
;             f16x8 xh[2][4][2];
; #pragma unroll
;             for (int ai = 0; ai < 2; ++ai)
; #pragma unroll
;                 for (int m = 0; m < 4; ++m)
; #pragma unroll
;                     for (int bj = 0; bj < 2; ++bj) xh[ai][m][bj] = *(const f16x8*)(XH + (size_t)(row0 + ai * 128 + m * 16) * DM + col0 + bj * 32);
; #pragma unroll
;             for (int ai = 0; ai < 2; ++ai)
; #pragma unroll
;                 for (int m = 0; m < 4; ++m) {
;                     float* dst = out + (size_t)(row0 + ai * 128 + m * 16) * DM + col0;
; #pragma unroll
;                     for (int bj = 0; bj < 2; ++bj) {
;                         f32x4 x0, x1;
; #pragma unroll
;                         for (int e = 0; e < 4; ++e) { x0[e] = (float)xh[ai][m][bj][e] + acc[ai][bj][m][0][e]; x1[e] = (float)xh[ai][m][bj][4 + e] + acc[ai][bj][m][1][e]; }
;                         *(f32x4*)(dst + bj * 32) = x0; *(f32x4*)(dst + bj * 32 + 4) = x1;
;                     }
;                 }
	v_mov_b32_dpp v93, v239 row_ror:8 row_mask:0xf bank_mask:0x3
	global_store_dwordx4 v[196:197], v[94:97], off
	global_store_dwordx4 v[192:193], v[90:93], off
	v_permlane16_swap_b32_e32 v86, v82
	v_permlane16_swap_b32_e32 v87, v83
	v_permlane16_swap_b32_e32 v88, v84
	v_permlane16_swap_b32_e32 v89, v85
	v_permlane32_swap_b32_e32 v86, v82
	v_permlane32_swap_b32_e32 v87, v83
	v_permlane32_swap_b32_e32 v88, v84
	v_permlane32_swap_b32_e32 v89, v85
	v_mov_b32_e32 v236, v86
	v_mov_b32_e32 v237, v87
	v_mov_b32_e32 v238, v88
	v_mov_b32_e32 v239, v89
	v_mov_b32_dpp v86, v82 row_ror:8 row_mask:0xf bank_mask:0xc
	v_mov_b32_dpp v87, v83 row_ror:8 row_mask:0xf bank_mask:0xc
	v_mov_b32_dpp v88, v84 row_ror:8 row_mask:0xf bank_mask:0xc
	v_mov_b32_dpp v89, v85 row_ror:8 row_mask:0xf bank_mask:0xc
	v_mov_b32_dpp v82, v236 row_ror:8 row_mask:0xf bank_mask:0x3
	v_mov_b32_dpp v83, v237 row_ror:8 row_mask:0xf bank_mask:0x3
	v_mov_b32_dpp v84, v238 row_ror:8 row_mask:0xf bank_mask:0x3
	v_mov_b32_dpp v85, v239 row_ror:8 row_mask:0xf bank_mask:0x3
	global_store_dwordx4 v[196:197], v[86:89], off offset:128
	global_store_dwordx4 v[192:193], v[82:85], off offset:128
	v_lshl_add_u64 v[196:197], v[196:197], 0, s[100:101]
	v_lshl_add_u64 v[192:193], v[192:193], 0, s[100:101]
	v_permlane16_swap_b32_e32 v78, v74
	v_permlane16_swap_b32_e32 v79, v75
	v_permlane16_swap_b32_e32 v80, v76
	v_permlane16_swap_b32_e32 v81, v77
	v_permlane32_swap_b32_e32 v78, v74
	v_permlane32_swap_b32_e32 v79, v75
	v_permlane32_swap_b32_e32 v80, v76
	v_permlane32_swap_b32_e32 v81, v77
	v_mov_b32_e32 v236, v78
	v_mov_b32_e32 v237, v79
	v_mov_b32_e32 v238, v80
	v_mov_b32_e32 v239, v81
	v_mov_b32_dpp v78, v74 row_ror:8 row_mask:0xf bank_mask:0xc
	v_mov_b32_dpp v79, v75 row_ror:8 row_mask:0xf bank_mask:0xc
	v_mov_b32_dpp v80, v76 row_ror:8 row_mask:0xf bank_mask:0xc
	v_mov_b32_dpp v81, v77 row_ror:8 row_mask:0xf bank_mask:0xc
	v_mov_b32_dpp v74, v236 row_ror:8 row_mask:0xf bank_mask:0x3
	v_mov_b32_dpp v75, v237 row_ror:8 row_mask:0xf bank_mask:0x3
	v_mov_b32_dpp v76, v238 row_ror:8 row_mask:0xf bank_mask:0x3
	v_mov_b32_dpp v77, v239 row_ror:8 row_mask:0xf bank_mask:0x3
	global_store_dwordx4 v[196:197], v[78:81], off
	global_store_dwordx4 v[192:193], v[74:77], off
	v_permlane16_swap_b32_e32 v70, v66
	v_permlane16_swap_b32_e32 v71, v67
	v_permlane16_swap_b32_e32 v72, v68
	v_permlane16_swap_b32_e32 v73, v69
	v_permlane32_swap_b32_e32 v70, v66
	v_permlane32_swap_b32_e32 v71, v67
	v_permlane32_swap_b32_e32 v72, v68
	v_permlane32_swap_b32_e32 v73, v69
	v_mov_b32_e32 v236, v70
	v_mov_b32_e32 v237, v71
	v_mov_b32_e32 v238, v72
	v_mov_b32_e32 v239, v73
	v_mov_b32_dpp v70, v66 row_ror:8 row_mask:0xf bank_mask:0xc
	v_mov_b32_dpp v71, v67 row_ror:8 row_mask:0xf bank_mask:0xc
	v_mov_b32_dpp v72, v68 row_ror:8 row_mask:0xf bank_mask:0xc
	v_mov_b32_dpp v73, v69 row_ror:8 row_mask:0xf bank_mask:0xc
	v_mov_b32_dpp v66, v236 row_ror:8 row_mask:0xf bank_mask:0x3
	v_mov_b32_dpp v67, v237 row_ror:8 row_mask:0xf bank_mask:0x3
	v_mov_b32_dpp v68, v238 row_ror:8 row_mask:0xf bank_mask:0x3
	v_mov_b32_dpp v69, v239 row_ror:8 row_mask:0xf bank_mask:0x3
	global_store_dwordx4 v[196:197], v[70:73], off offset:128
	global_store_dwordx4 v[192:193], v[66:69], off offset:128
	s_mov_b64 s[100:101], 0x50000
	v_lshl_add_u64 v[196:197], v[196:197], 0, s[100:101]
	v_lshl_add_u64 v[192:193], v[192:193], 0, s[100:101]
	s_mov_b64 s[100:101], 0x10000
	v_permlane16_swap_b32_e32 v62, v58
	v_permlane16_swap_b32_e32 v63, v59
	v_permlane16_swap_b32_e32 v64, v60
	v_permlane16_swap_b32_e32 v65, v61
	v_permlane32_swap_b32_e32 v62, v58
	v_permlane32_swap_b32_e32 v63, v59
	v_permlane32_swap_b32_e32 v64, v60
	v_permlane32_swap_b32_e32 v65, v61
	v_mov_b32_e32 v236, v62
	v_mov_b32_e32 v237, v63
	v_mov_b32_e32 v238, v64
	v_mov_b32_e32 v239, v65
	v_mov_b32_dpp v62, v58 row_ror:8 row_mask:0xf bank_mask:0xc
	v_mov_b32_dpp v63, v59 row_ror:8 row_mask:0xf bank_mask:0xc
	v_mov_b32_dpp v64, v60 row_ror:8 row_mask:0xf bank_mask:0xc
	v_mov_b32_dpp v65, v61 row_ror:8 row_mask:0xf bank_mask:0xc
	v_mov_b32_dpp v58, v236 row_ror:8 row_mask:0xf bank_mask:0x3
	v_mov_b32_dpp v59, v237 row_ror:8 row_mask:0xf bank_mask:0x3
	v_mov_b32_dpp v60, v238 row_ror:8 row_mask:0xf bank_mask:0x3
	v_mov_b32_dpp v61, v239 row_ror:8 row_mask:0xf bank_mask:0x3
	global_store_dwordx4 v[196:197], v[62:65], off
	global_store_dwordx4 v[192:193], v[58:61], off
	v_permlane16_swap_b32_e32 v54, v50
	v_permlane16_swap_b32_e32 v55, v51
	v_permlane16_swap_b32_e32 v56, v52
	v_permlane16_swap_b32_e32 v57, v53
	v_permlane32_swap_b32_e32 v54, v50
	v_permlane32_swap_b32_e32 v55, v51
	v_permlane32_swap_b32_e32 v56, v52
	v_permlane32_swap_b32_e32 v57, v53
	v_mov_b32_e32 v236, v54
	v_mov_b32_e32 v237, v55
	v_mov_b32_e32 v238, v56
	v_mov_b32_e32 v239, v57
	v_mov_b32_dpp v54, v50 row_ror:8 row_mask:0xf bank_mask:0xc
	v_mov_b32_dpp v55, v51 row_ror:8 row_mask:0xf bank_mask:0xc
	v_mov_b32_dpp v56, v52 row_ror:8 row_mask:0xf bank_mask:0xc
	v_mov_b32_dpp v57, v53 row_ror:8 row_mask:0xf bank_mask:0xc
	v_mov_b32_dpp v50, v236 row_ror:8 row_mask:0xf bank_mask:0x3
	v_mov_b32_dpp v51, v237 row_ror:8 row_mask:0xf bank_mask:0x3
	v_mov_b32_dpp v52, v238 row_ror:8 row_mask:0xf bank_mask:0x3
	v_mov_b32_dpp v53, v239 row_ror:8 row_mask:0xf bank_mask:0x3
	global_store_dwordx4 v[196:197], v[54:57], off offset:128
	global_store_dwordx4 v[192:193], v[50:53], off offset:128
	v_lshl_add_u64 v[196:197], v[196:197], 0, s[100:101]
	v_lshl_add_u64 v[192:193], v[192:193], 0, s[100:101]
	v_permlane16_swap_b32_e32 v46, v42
	v_permlane16_swap_b32_e32 v47, v43
	v_permlane16_swap_b32_e32 v48, v44
	v_permlane16_swap_b32_e32 v49, v45
;     __device__ __forceinline__ void operator()(const f32x4 (&acc)[2][2][4][2], const pg8::Unit& u, int, LAS unsigned char*, int wr, int wc, int fr_, int fq_) const {
;     ...
;         } else {
;             f16x8 xh[2][4][2];
; #pragma unroll
;             for (int ai = 0; ai < 2; ++ai)
; #pragma unroll
;                 for (int m = 0; m < 4; ++m)
; #pragma unroll
;                     for (int bj = 0; bj < 2; ++bj) xh[ai][m][bj] = *(const f16x8*)(XH + (size_t)(row0 + ai * 128 + m * 16) * DM + col0 + bj * 32);
; #pragma unroll
;             for (int ai = 0; ai < 2; ++ai)
; #pragma unroll
;                 for (int m = 0; m < 4; ++m) {
;                     float* dst = out + (size_t)(row0 + ai * 128 + m * 16) * DM + col0;
; #pragma unroll
;                     for (int bj = 0; bj < 2; ++bj) {
;                         f32x4 x0, x1;
; #pragma unroll
;                         for (int e = 0; e < 4; ++e) { x0[e] = (float)xh[ai][m][bj][e] + acc[ai][bj][m][0][e]; x1[e] = (float)xh[ai][m][bj][4 + e] + acc[ai][bj][m][1][e]; }
;                         *(f32x4*)(dst + bj * 32) = x0; *(f32x4*)(dst + bj * 32 + 4) = x1;
;                     }
;                 }
	v_permlane32_swap_b32_e32 v46, v42
	v_permlane32_swap_b32_e32 v47, v43
	v_permlane32_swap_b32_e32 v48, v44
	v_permlane32_swap_b32_e32 v49, v45
	v_mov_b32_e32 v236, v46
	v_mov_b32_e32 v237, v47
	v_mov_b32_e32 v238, v48
	v_mov_b32_e32 v239, v49
	v_mov_b32_dpp v46, v42 row_ror:8 row_mask:0xf bank_mask:0xc
	v_mov_b32_dpp v47, v43 row_ror:8 row_mask:0xf bank_mask:0xc
	v_mov_b32_dpp v48, v44 row_ror:8 row_mask:0xf bank_mask:0xc
	v_mov_b32_dpp v49, v45 row_ror:8 row_mask:0xf bank_mask:0xc
	v_mov_b32_dpp v42, v236 row_ror:8 row_mask:0xf bank_mask:0x3
	v_mov_b32_dpp v43, v237 row_ror:8 row_mask:0xf bank_mask:0x3
	v_mov_b32_dpp v44, v238 row_ror:8 row_mask:0xf bank_mask:0x3
	v_mov_b32_dpp v45, v239 row_ror:8 row_mask:0xf bank_mask:0x3
	global_store_dwordx4 v[196:197], v[46:49], off
	global_store_dwordx4 v[192:193], v[42:45], off
	v_permlane16_swap_b32_e32 v38, v34
	v_permlane16_swap_b32_e32 v39, v35
	v_permlane16_swap_b32_e32 v40, v36
	v_permlane16_swap_b32_e32 v41, v37
	v_permlane32_swap_b32_e32 v38, v34
	v_permlane32_swap_b32_e32 v39, v35
	v_permlane32_swap_b32_e32 v40, v36
	v_permlane32_swap_b32_e32 v41, v37
	v_mov_b32_e32 v236, v38
	v_mov_b32_e32 v237, v39
	v_mov_b32_e32 v238, v40
	v_mov_b32_e32 v239, v41
	v_mov_b32_dpp v38, v34 row_ror:8 row_mask:0xf bank_mask:0xc
	v_mov_b32_dpp v39, v35 row_ror:8 row_mask:0xf bank_mask:0xc
	v_mov_b32_dpp v40, v36 row_ror:8 row_mask:0xf bank_mask:0xc
	v_mov_b32_dpp v41, v37 row_ror:8 row_mask:0xf bank_mask:0xc
	v_mov_b32_dpp v34, v236 row_ror:8 row_mask:0xf bank_mask:0x3
	v_mov_b32_dpp v35, v237 row_ror:8 row_mask:0xf bank_mask:0x3
	v_mov_b32_dpp v36, v238 row_ror:8 row_mask:0xf bank_mask:0x3
	v_mov_b32_dpp v37, v239 row_ror:8 row_mask:0xf bank_mask:0x3
	global_store_dwordx4 v[196:197], v[38:41], off offset:128
	global_store_dwordx4 v[192:193], v[34:37], off offset:128
	v_lshl_add_u64 v[196:197], v[196:197], 0, s[100:101]
	v_lshl_add_u64 v[192:193], v[192:193], 0, s[100:101]
	v_permlane16_swap_b32_e32 v30, v26
	v_permlane16_swap_b32_e32 v31, v27
	v_permlane16_swap_b32_e32 v32, v28
	v_permlane16_swap_b32_e32 v33, v29
	v_permlane32_swap_b32_e32 v30, v26
	v_permlane32_swap_b32_e32 v31, v27
	v_permlane32_swap_b32_e32 v32, v28
	v_permlane32_swap_b32_e32 v33, v29
	v_mov_b32_e32 v236, v30
	v_mov_b32_e32 v237, v31
	v_mov_b32_e32 v238, v32
	v_mov_b32_e32 v239, v33
	v_mov_b32_dpp v30, v26 row_ror:8 row_mask:0xf bank_mask:0xc
	v_mov_b32_dpp v31, v27 row_ror:8 row_mask:0xf bank_mask:0xc
	v_mov_b32_dpp v32, v28 row_ror:8 row_mask:0xf bank_mask:0xc
	v_mov_b32_dpp v33, v29 row_ror:8 row_mask:0xf bank_mask:0xc
	v_mov_b32_dpp v26, v236 row_ror:8 row_mask:0xf bank_mask:0x3
	v_mov_b32_dpp v27, v237 row_ror:8 row_mask:0xf bank_mask:0x3
	v_mov_b32_dpp v28, v238 row_ror:8 row_mask:0xf bank_mask:0x3
	v_mov_b32_dpp v29, v239 row_ror:8 row_mask:0xf bank_mask:0x3
	global_store_dwordx4 v[196:197], v[30:33], off
	global_store_dwordx4 v[192:193], v[26:29], off
	v_permlane16_swap_b32_e32 v22, v18
	v_permlane16_swap_b32_e32 v23, v19
	v_permlane16_swap_b32_e32 v24, v20
	v_permlane16_swap_b32_e32 v25, v21
	v_permlane32_swap_b32_e32 v22, v18
	v_permlane32_swap_b32_e32 v23, v19
	v_permlane32_swap_b32_e32 v24, v20
	v_permlane32_swap_b32_e32 v25, v21
	v_mov_b32_e32 v236, v22
	v_mov_b32_e32 v237, v23
	v_mov_b32_e32 v238, v24
	v_mov_b32_e32 v239, v25
	v_mov_b32_dpp v22, v18 row_ror:8 row_mask:0xf bank_mask:0xc
	v_mov_b32_dpp v23, v19 row_ror:8 row_mask:0xf bank_mask:0xc
	v_mov_b32_dpp v24, v20 row_ror:8 row_mask:0xf bank_mask:0xc
	v_mov_b32_dpp v25, v21 row_ror:8 row_mask:0xf bank_mask:0xc
	v_mov_b32_dpp v18, v236 row_ror:8 row_mask:0xf bank_mask:0x3
	v_mov_b32_dpp v19, v237 row_ror:8 row_mask:0xf bank_mask:0x3
	v_mov_b32_dpp v20, v238 row_ror:8 row_mask:0xf bank_mask:0x3
	v_mov_b32_dpp v21, v239 row_ror:8 row_mask:0xf bank_mask:0x3
	global_store_dwordx4 v[196:197], v[22:25], off offset:128
	global_store_dwordx4 v[192:193], v[18:21], off offset:128
	v_lshl_add_u64 v[196:197], v[196:197], 0, s[100:101]
	v_lshl_add_u64 v[192:193], v[192:193], 0, s[100:101]
	v_permlane16_swap_b32_e32 v14, v10
	v_permlane16_swap_b32_e32 v15, v11
	v_permlane16_swap_b32_e32 v16, v12
	v_permlane16_swap_b32_e32 v17, v13
	v_permlane32_swap_b32_e32 v14, v10
	v_permlane32_swap_b32_e32 v15, v11
	v_permlane32_swap_b32_e32 v16, v12
	v_permlane32_swap_b32_e32 v17, v13
	v_mov_b32_e32 v236, v14
	v_mov_b32_e32 v237, v15
	v_mov_b32_e32 v238, v16
	v_mov_b32_e32 v239, v17
	v_mov_b32_dpp v14, v10 row_ror:8 row_mask:0xf bank_mask:0xc
	v_mov_b32_dpp v15, v11 row_ror:8 row_mask:0xf bank_mask:0xc
	v_mov_b32_dpp v16, v12 row_ror:8 row_mask:0xf bank_mask:0xc
	v_mov_b32_dpp v17, v13 row_ror:8 row_mask:0xf bank_mask:0xc
	v_mov_b32_dpp v10, v236 row_ror:8 row_mask:0xf bank_mask:0x3
	v_mov_b32_dpp v11, v237 row_ror:8 row_mask:0xf bank_mask:0x3
	v_mov_b32_dpp v12, v238 row_ror:8 row_mask:0xf bank_mask:0x3
	v_mov_b32_dpp v13, v239 row_ror:8 row_mask:0xf bank_mask:0x3
	global_store_dwordx4 v[196:197], v[14:17], off
	global_store_dwordx4 v[192:193], v[10:13], off
	v_permlane16_swap_b32_e32 v6, v2
	v_permlane16_swap_b32_e32 v7, v3
	v_permlane16_swap_b32_e32 v8, v4
	v_permlane16_swap_b32_e32 v9, v5
	v_permlane32_swap_b32_e32 v6, v2
	v_permlane32_swap_b32_e32 v7, v3
	v_permlane32_swap_b32_e32 v8, v4
	v_permlane32_swap_b32_e32 v9, v5
	v_mov_b32_e32 v236, v6
	v_mov_b32_e32 v237, v7
	v_mov_b32_e32 v238, v8
	v_mov_b32_e32 v239, v9
	v_mov_b32_dpp v6, v2 row_ror:8 row_mask:0xf bank_mask:0xc
	v_mov_b32_dpp v7, v3 row_ror:8 row_mask:0xf bank_mask:0xc
	v_mov_b32_dpp v8, v4 row_ror:8 row_mask:0xf bank_mask:0xc
	v_mov_b32_dpp v9, v5 row_ror:8 row_mask:0xf bank_mask:0xc
	v_mov_b32_dpp v2, v236 row_ror:8 row_mask:0xf bank_mask:0x3
	v_mov_b32_dpp v3, v237 row_ror:8 row_mask:0xf bank_mask:0x3
	v_mov_b32_dpp v4, v238 row_ror:8 row_mask:0xf bank_mask:0x3
	v_mov_b32_dpp v5, v239 row_ror:8 row_mask:0xf bank_mask:0x3
	global_store_dwordx4 v[196:197], v[6:9], off offset:128
	global_store_dwordx4 v[192:193], v[2:5], off offset:128
	s_branch .LBB0_502
